# scan pass 1 (P and L transition products) operands via LDS-DMA ring + broadcast ds_read instead of scalar loads, on top of v5
# speedup vs baseline: 1.0144x; 1.0144x over previous
; __device__ __forceinline__ void scan_pass1(const Ctx&, unsigned char* ws, int rot) { const Ctx c = mk_ctx();
;     ...
;     for (int task = (int)((blockIdx.x + (rot ? gridDim.x / 2 : 0)) % gridDim.x) * 4 + c.wid; task < 16 * (NCH - 1); task += gridDim.x * 4) {
;         const int cc = task % (NCH - 1), chain = task / (NCH - 1);
;         f32x2 SP[32], SLs[32];
; #pragma unroll
;         for (int j = 0; j < 32; ++j) { SP[j].x = (2 * j == lane) ? 1.f : 0.f; SP[j].y = (2 * j + 1 == lane) ? 1.f : 0.f; SLs[j] = (f32x2){0.f, 0.f}; }
;         cfloat* ob = (cfloat*)(scanop + ((size_t)chain * SEQ + (size_t)cc * CHL) * 320);
;         const float* og = scanop + ((size_t)chain * SEQ + (size_t)cc * CHL) * 320;
;         const bf16* vp = vbf + ((size_t)chain * SEQ + (size_t)cc * CHL) * 64 + lane;
;         f32x4 pfa = {0.f, 0.f, 0.f, 0.f}; float pfb = 0.f; unsigned short vnext = vp[0];
;         for (int t = 0; t < CHL; ++t) { cfloat* o = ob + (size_t)t * 320;
;             const unsigned short vcur = vnext; pfdummy += pfa[0] + pfb;
;             vnext = vp[(size_t)(t + 1) * 64];
;             pfa = *(const f32x4*)(og + (size_t)(t + SCAN_PF) * 320 + lane * 4); pfb = og[(size_t)(t + SCAN_PF) * 320 + 256 + lane];
.LBB0_1917:
	s_mul_hi_i32 s4, s33, 0x82082083
	s_add_i32 s4, s4, s33
	s_lshr_b32 s5, s4, 31
	s_ashr_i32 s4, s4, 5
	s_add_i32 s26, s4, s5
	s_mul_i32 s4, s26, 63
	s_sub_i32 s24, s33, s4
	s_ashr_i32 s27, s26, 31
	s_ashr_i32 s25, s24, 31
	s_lshl_b64 s[4:5], s[26:27], 13
	s_lshl_b64 s[6:7], s[24:25], 7
	s_add_u32 s4, s4, s6
	s_addc_u32 s5, s5, s7
	s_mul_i32 s8, s5, 0x500
	s_mul_hi_u32 s6, s4, 0x500
	s_add_i32 s6, s6, s8
	s_mul_i32 s7, s4, 0x500
	s_add_u32 s36, s34, s7
	s_addc_u32 s37, s35, s6
	s_lshl_b64 s[6:7], s[4:5], 7
	v_lshl_add_u64 v[2:3], v[134:135], 0, s[6:7]
	v_lshl_add_u64 v[142:143], v[136:137], 0, s[6:7]
	v_mad_u64_u32 v[144:145], s[6:7], s4, v211, v[138:139]
	v_mad_u64_u32 v[154:155], s[4:5], s4, v211, v[140:141]
	v_add_u32_e32 v145, s8, v145
	v_add_u32_e32 v155, s8, v155
	s_mov_b64 s[28:29], 0
	v_mov_b32_e32 v131, 0
	v_mov_b32_e32 v4, v241
	v_mov_b32_e32 v5, v242
	v_mov_b32_e32 v2, v239
	v_mov_b32_e32 v3, v240
	v_mov_b32_e32 v8, v237
	v_mov_b32_e32 v9, v238
	v_mov_b32_e32 v6, v235
	v_mov_b32_e32 v7, v236
	v_mov_b32_e32 v12, v233
	v_mov_b32_e32 v13, v234
	v_mov_b32_e32 v10, v231
	v_mov_b32_e32 v11, v232
	v_mov_b32_e32 v16, v229
	v_mov_b32_e32 v17, v230
	v_mov_b32_e32 v14, v227
	v_mov_b32_e32 v15, v228
	v_mov_b32_e32 v24, v225
	v_mov_b32_e32 v25, v226
	v_mov_b32_e32 v22, v223
	v_mov_b32_e32 v23, v224
	v_mov_b32_e32 v28, v221
	v_mov_b32_e32 v29, v222
	v_mov_b32_e32 v26, v219
	v_mov_b32_e32 v27, v220
	v_mov_b32_e32 v36, v217
	v_mov_b32_e32 v37, v218
	v_mov_b32_e32 v34, v215
	v_mov_b32_e32 v35, v216
	v_mov_b32_e32 v44, v193
	v_mov_b32_e32 v45, v214
	v_mov_b32_e32 v42, v191
	v_mov_b32_e32 v43, v192
	v_mov_b32_e32 v52, v189
	v_mov_b32_e32 v53, v190
	v_mov_b32_e32 v50, v187
	v_mov_b32_e32 v51, v188
	v_mov_b32_e32 v60, v185
	v_mov_b32_e32 v61, v186
	v_mov_b32_e32 v58, v183
	v_mov_b32_e32 v59, v184
	v_mov_b32_e32 v68, v181
	v_mov_b32_e32 v69, v182
	v_mov_b32_e32 v66, v179
	v_mov_b32_e32 v67, v180
	v_mov_b32_e32 v76, v177
	v_mov_b32_e32 v77, v178
	v_mov_b32_e32 v74, v175
	v_mov_b32_e32 v75, v176
	v_mov_b32_e32 v84, v173
	v_mov_b32_e32 v85, v174
	v_mov_b32_e32 v82, v171
	v_mov_b32_e32 v83, v172
	v_mov_b32_e32 v92, v169
	v_mov_b32_e32 v93, v170
	v_mov_b32_e32 v90, v167
	v_mov_b32_e32 v91, v168
	v_mov_b32_e32 v100, v165
	v_mov_b32_e32 v101, v166
	v_mov_b32_e32 v98, v163
	v_mov_b32_e32 v99, v164
	v_mov_b32_e32 v112, v161
	v_mov_b32_e32 v113, v162
	v_mov_b32_e32 v110, v1
	v_mov_b32_e32 v111, v160
	v_mov_b32_e32 v20, 0
	v_mov_b32_e32 v21, v243
	v_mov_b32_e32 v18, 0
	v_mov_b32_e32 v19, v243
	v_mov_b32_e32 v32, 0
	v_mov_b32_e32 v33, v243
	v_mov_b32_e32 v30, 0
	v_mov_b32_e32 v31, v243
	v_mov_b32_e32 v40, 0
	v_mov_b32_e32 v41, v243
	v_mov_b32_e32 v38, 0
	v_mov_b32_e32 v39, v243
	v_mov_b32_e32 v48, 0
	v_mov_b32_e32 v49, v243
	v_mov_b32_e32 v46, 0
	v_mov_b32_e32 v47, v243
	v_mov_b32_e32 v56, 0
	v_mov_b32_e32 v57, v243
	v_mov_b32_e32 v54, 0
	v_mov_b32_e32 v55, v243
	v_mov_b32_e32 v64, 0
	v_mov_b32_e32 v65, v243
	v_mov_b32_e32 v62, 0
	v_mov_b32_e32 v63, v243
	v_mov_b32_e32 v72, 0
	v_mov_b32_e32 v73, v243
	v_mov_b32_e32 v70, 0
	v_mov_b32_e32 v71, v243
	v_mov_b32_e32 v80, 0
	v_mov_b32_e32 v81, v243
	v_mov_b32_e32 v78, 0
	v_mov_b32_e32 v79, v243
	v_mov_b32_e32 v88, 0
	v_mov_b32_e32 v89, v243
	v_mov_b32_e32 v86, 0
	v_mov_b32_e32 v87, v243
	v_mov_b32_e32 v96, 0
	v_mov_b32_e32 v97, v243
	v_mov_b32_e32 v94, 0
	v_mov_b32_e32 v95, v243
	v_mov_b32_e32 v104, 0
	v_mov_b32_e32 v105, v243
	v_mov_b32_e32 v102, 0
	v_mov_b32_e32 v103, v243
	v_mov_b32_e32 v108, 0
	v_mov_b32_e32 v109, v243
	v_mov_b32_e32 v106, 0
	v_mov_b32_e32 v107, v243
	v_mov_b32_e32 v116, 0
	v_mov_b32_e32 v117, v243
	v_mov_b32_e32 v114, 0
	v_mov_b32_e32 v115, v243
	v_mov_b32_e32 v120, 0
	v_mov_b32_e32 v121, v243
	v_mov_b32_e32 v118, 0
	v_mov_b32_e32 v119, v243
	v_mov_b32_e32 v124, 0
	v_mov_b32_e32 v125, v243
	v_mov_b32_e32 v122, 0
	v_mov_b32_e32 v123, v243
	v_mov_b32_e32 v128, 0
	v_mov_b32_e32 v129, v243
	v_mov_b32_e32 v126, 0
	v_mov_b32_e32 v127, v243
	v_mov_b32_e32 v130, 0
	v_readfirstlane_b32 s44, v147
	s_mul_i32 s44, s44, 0xa0
	s_add_i32 s44, s44, 0x4000
	s_mov_b32 s30, 0
	v_lshlrev_b32_e32 v130, 1, v206
	v_add_u32_e32 v130, 0x180, v130
	v_mov_b32_e32 v131, 0
	v_lshl_add_u64 v[142:143], v[142:143], 0, v[130:131]
	s_mov_b32 s4, 0xffffec00
	s_mov_b32 s5, -1
	v_lshl_add_u64 v[130:131], v[144:145], 0, s[4:5]
	s_mov_b32 s4, 0xfffffe00
	v_lshl_add_u64 v[132:133], v[142:143], 0, s[4:5]
	s_mov_b64 s[4:5], 0x500
	s_mov_b64 s[6:7], 0x80
	s_add_i32 m0, s44, 0x0
	s_nop 0
	global_load_lds_dwordx4 v[130:131], off
	s_add_i32 m0, s44, 0x400
	s_nop 0
	global_load_lds_dword v[132:133], off
	v_lshl_add_u64 v[130:131], v[130:131], 0, s[4:5]
	v_lshl_add_u64 v[132:133], v[132:133], 0, s[6:7]
	s_add_i32 m0, s44, 0x500
	s_nop 0
	global_load_lds_dwordx4 v[130:131], off
	s_add_i32 m0, s44, 0x900
	s_nop 0
	global_load_lds_dword v[132:133], off
	v_lshl_add_u64 v[130:131], v[130:131], 0, s[4:5]
	v_lshl_add_u64 v[132:133], v[132:133], 0, s[6:7]
	s_add_i32 m0, s44, 0xa00
	s_nop 0
	global_load_lds_dwordx4 v[130:131], off
	s_add_i32 m0, s44, 0xe00
	s_nop 0
	global_load_lds_dword v[132:133], off
	v_lshl_add_u64 v[130:131], v[130:131], 0, s[4:5]
	v_lshl_add_u64 v[132:133], v[132:133], 0, s[6:7]
	s_add_i32 m0, s44, 0xf00
	s_nop 0
	global_load_lds_dwordx4 v[130:131], off
	s_add_i32 m0, s44, 0x1300
	s_nop 0
	global_load_lds_dword v[132:133], off
; #define SL4(a, b, c, d, p, o0, o1, o2, o3) asm volatile("s_load_dwordx16 %0, %4, %5\n\ts_load_dwordx16 %1, %4, %6\n\ts_load_dwordx16 %2, %4, %7\n\ts_load_dwordx16 %3, %4, %8\n\ts_waitcnt lgkmcnt(0)" : "=&s"(a), "=&s"(b), "=&s"(c), "=&s"(d) : "s"(p), "i"(o0), "i"(o1), "i"(o2), "i"(o3) : "memory")
; __device__ __forceinline__ void scan_pass1(const Ctx&, unsigned char* ws, int rot) { const Ctx c = mk_ctx();
;     ...
;         for (int t = 0; t < CHL; ++t) { cfloat* o = ob + (size_t)t * 320;
;             const unsigned short vcur = vnext; pfdummy += pfa[0] + pfb;
;             vnext = vp[(size_t)(t + 1) * 64];
;             pfa = *(const f32x4*)(og + (size_t)(t + SCAN_PF) * 320 + lane * 4); pfb = og[(size_t)(t + SCAN_PF) * 320 + 256 + lane];
;             float saP, saL;
;             { f32x16s k0_, k1_, k2_, k3_; SL4(k0_, k1_, k2_, k3_, o, 0, 64, 128, 192); f32x2 a2 = {0.f, 0.f}, b2 = {0.f, 0.f};
; #pragma unroll
;               for (int p_ = 0; p_ < 8; ++p_) { a2 += SP[p_] * PR(k0_, p_); b2 += SLs[p_] * PR(k0_, p_); a2 += SP[8 + p_] * PR(k1_, p_); b2 += SLs[8 + p_] * PR(k1_, p_);
;                   a2 += SP[16 + p_] * PR(k2_, p_); b2 += SLs[16 + p_] * PR(k2_, p_); a2 += SP[24 + p_] * PR(k3_, p_); b2 += SLs[24 + p_] * PR(k3_, p_); }
;               saP = -(a2.x + a2.y); saL = -(b2.x + b2.y); }
;             const f32x2 savP = {saP, saP}, savL = {saL, saL}; const float v = __builtin_bit_cast(float, (unsigned)vcur << 16); const f32x2 vv = {v, v};
.LBB0_1918:
	v_readfirstlane_b32 s44, v147
	s_mul_i32 s44, s44, 0xa0
	s_add_i32 s44, s44, 0x4000
	s_add_i32 s45, s30, 4
	s_and_b32 s45, s45, 7
	s_mul_i32 s45, s45, 0x500
	s_add_i32 s45, s45, s44
	s_and_b32 s46, s30, 7
	s_mul_i32 s46, s46, 0x500
	s_add_i32 s46, s46, s44
	v_lshl_add_u64 v[130:131], v[144:145], 0, s[28:29]
	s_mov_b32 m0, s45
	s_nop 0
	global_load_lds_dwordx4 v[130:131], off
	s_add_i32 m0, s45, 0x400
	s_nop 0
	global_load_lds_dword v[142:143], off
	s_waitcnt vmcnt(8)
	v_mov_b32_e32 v232, s46
	v_lshl_add_u32 v233, v206, 1, s46
	ds_read_u16 v245, v233 offset:1024
	ds_read_b128 v[160:163], v232
	ds_read_b128 v[164:167], v232 offset:16
	ds_read_b128 v[168:171], v232 offset:32
	ds_read_b128 v[172:175], v232 offset:48
	ds_read_b128 v[176:179], v232 offset:64
	ds_read_b128 v[180:183], v232 offset:80
	ds_read_b128 v[184:187], v232 offset:96
	ds_read_b128 v[188:191], v232 offset:112
	ds_read_b128 v[214:217], v232 offset:128
	ds_read_b128 v[218:221], v232 offset:144
	ds_read_b128 v[222:225], v232 offset:160
	ds_read_b128 v[226:229], v232 offset:176
	s_waitcnt lgkmcnt(8)
	v_pk_fma_f32 v[132:133], v[110:111], v[160:161], 0 op_sel_hi:[1,1,0]
	v_pk_fma_f32 v[156:157], v[126:127], v[160:161], 0 op_sel_hi:[1,1,0]
	v_pk_fma_f32 v[132:133], v[112:113], v[162:163], v[132:133]
	v_pk_fma_f32 v[156:157], v[128:129], v[162:163], v[156:157]
	v_pk_fma_f32 v[132:133], v[98:99], v[164:165], v[132:133]
	v_pk_fma_f32 v[156:157], v[122:123], v[164:165], v[156:157]
	v_pk_fma_f32 v[132:133], v[100:101], v[166:167], v[132:133]
	v_pk_fma_f32 v[156:157], v[124:125], v[166:167], v[156:157]
	v_pk_fma_f32 v[132:133], v[90:91], v[168:169], v[132:133]
	v_pk_fma_f32 v[156:157], v[118:119], v[168:169], v[156:157]
	v_pk_fma_f32 v[132:133], v[92:93], v[170:171], v[132:133]
	v_pk_fma_f32 v[156:157], v[120:121], v[170:171], v[156:157]
	v_pk_fma_f32 v[132:133], v[82:83], v[172:173], v[132:133]
	v_pk_fma_f32 v[156:157], v[114:115], v[172:173], v[156:157]
	v_pk_fma_f32 v[132:133], v[84:85], v[174:175], v[132:133]
	v_pk_fma_f32 v[156:157], v[116:117], v[174:175], v[156:157]
	ds_read_b128 v[160:163], v232 offset:192
	ds_read_b128 v[164:167], v232 offset:208
	ds_read_b128 v[168:171], v232 offset:224
	ds_read_b128 v[172:175], v232 offset:240
	s_waitcnt lgkmcnt(8)
	v_pk_fma_f32 v[132:133], v[74:75], v[176:177], v[132:133]
	v_pk_fma_f32 v[156:157], v[106:107], v[176:177], v[156:157]
	v_pk_fma_f32 v[132:133], v[76:77], v[178:179], v[132:133]
	v_pk_fma_f32 v[156:157], v[108:109], v[178:179], v[156:157]
	v_pk_fma_f32 v[132:133], v[66:67], v[180:181], v[132:133]
	v_pk_fma_f32 v[156:157], v[102:103], v[180:181], v[156:157]
	v_pk_fma_f32 v[132:133], v[68:69], v[182:183], v[132:133]
	v_pk_fma_f32 v[156:157], v[104:105], v[182:183], v[156:157]
	v_pk_fma_f32 v[132:133], v[58:59], v[184:185], v[132:133]
	v_pk_fma_f32 v[156:157], v[94:95], v[184:185], v[156:157]
	v_pk_fma_f32 v[132:133], v[60:61], v[186:187], v[132:133]
	v_pk_fma_f32 v[156:157], v[96:97], v[186:187], v[156:157]
	v_pk_fma_f32 v[132:133], v[50:51], v[188:189], v[132:133]
	v_pk_fma_f32 v[156:157], v[86:87], v[188:189], v[156:157]
	v_pk_fma_f32 v[132:133], v[52:53], v[190:191], v[132:133]
	v_pk_fma_f32 v[156:157], v[88:89], v[190:191], v[156:157]
	ds_read_b128 v[176:179], v232 offset:256
	ds_read_b128 v[180:183], v232 offset:512
	ds_read_b128 v[184:187], v232 offset:768
	ds_read_b128 v[188:191], v232 offset:272
	s_waitcnt lgkmcnt(8)
	v_pk_fma_f32 v[132:133], v[42:43], v[214:215], v[132:133]
	v_pk_fma_f32 v[156:157], v[78:79], v[214:215], v[156:157]
	v_pk_fma_f32 v[132:133], v[44:45], v[216:217], v[132:133]
	v_pk_fma_f32 v[156:157], v[80:81], v[216:217], v[156:157]
	v_pk_fma_f32 v[132:133], v[34:35], v[218:219], v[132:133]
	v_pk_fma_f32 v[156:157], v[70:71], v[218:219], v[156:157]
	v_pk_fma_f32 v[132:133], v[36:37], v[220:221], v[132:133]
	v_pk_fma_f32 v[156:157], v[72:73], v[220:221], v[156:157]
	v_pk_fma_f32 v[132:133], v[26:27], v[222:223], v[132:133]
	v_pk_fma_f32 v[156:157], v[62:63], v[222:223], v[156:157]
	v_pk_fma_f32 v[132:133], v[28:29], v[224:225], v[132:133]
	v_pk_fma_f32 v[156:157], v[64:65], v[224:225], v[156:157]
	v_pk_fma_f32 v[132:133], v[22:23], v[226:227], v[132:133]
	v_pk_fma_f32 v[156:157], v[54:55], v[226:227], v[156:157]
	v_pk_fma_f32 v[132:133], v[24:25], v[228:229], v[132:133]
	v_pk_fma_f32 v[156:157], v[56:57], v[228:229], v[156:157]
	ds_read_b128 v[214:217], v232 offset:528
	ds_read_b128 v[218:221], v232 offset:784
	ds_read_b128 v[222:225], v232 offset:288
	ds_read_b128 v[226:229], v232 offset:544
	s_waitcnt lgkmcnt(8)
	v_pk_fma_f32 v[132:133], v[14:15], v[160:161], v[132:133]
	v_pk_fma_f32 v[156:157], v[46:47], v[160:161], v[156:157]
	v_pk_fma_f32 v[132:133], v[16:17], v[162:163], v[132:133]
	v_pk_fma_f32 v[156:157], v[48:49], v[162:163], v[156:157]
	v_pk_fma_f32 v[132:133], v[10:11], v[164:165], v[132:133]
	v_pk_fma_f32 v[156:157], v[38:39], v[164:165], v[156:157]
	v_pk_fma_f32 v[132:133], v[12:13], v[166:167], v[132:133]
	v_pk_fma_f32 v[156:157], v[40:41], v[166:167], v[156:157]
	v_pk_fma_f32 v[132:133], v[6:7], v[168:169], v[132:133]
	v_pk_fma_f32 v[156:157], v[30:31], v[168:169], v[156:157]
	v_pk_fma_f32 v[132:133], v[8:9], v[170:171], v[132:133]
	v_pk_fma_f32 v[156:157], v[32:33], v[170:171], v[156:157]
	v_pk_fma_f32 v[132:133], v[2:3], v[172:173], v[132:133]
	v_pk_fma_f32 v[156:157], v[18:19], v[172:173], v[156:157]
	v_pk_fma_f32 v[132:133], v[4:5], v[174:175], v[132:133]
	v_pk_fma_f32 v[156:157], v[20:21], v[174:175], v[156:157]
	v_pk_add_f32 v[158:159], v[132:133], v[132:133] op_sel:[0,1] op_sel_hi:[1,0]
	v_pk_add_f32 v[156:157], v[156:157], v[156:157] op_sel:[0,1] op_sel_hi:[1,0]
	v_lshlrev_b32_e32 v132, 16, v245
	ds_read_b128 v[160:163], v232 offset:800
	ds_read_b128 v[164:167], v232 offset:304
	ds_read_b128 v[168:171], v232 offset:560
	ds_read_b128 v[172:175], v232 offset:816
	s_waitcnt lgkmcnt(9)
; #define P1_BLK(b) { f32x16s w_, a_, k_; SL3(w_, a_, k_, o, 256 + 64 * (b), 512 + 64 * (b), 768 + 64 * (b)); _Pragma("unroll") for (int p_ = 0; p_ < 8; ++p_) { \
;                 f32x2 s = SP[8 * (b) + p_] * PR(w_, p_); s += savP * PR(a_, p_); SP[8 * (b) + p_] = s; \
;                 f32x2 l = SLs[8 * (b) + p_] * PR(w_, p_); l += savL * PR(a_, p_); l += vv * PR(k_, p_); SLs[8 * (b) + p_] = l; } }
; __device__ __forceinline__ void scan_pass1(const Ctx&, unsigned char* ws, int rot) { const Ctx c = mk_ctx();
;     ...
;             P1_BLK(0) P1_BLK(1) P1_BLK(2) P1_BLK(3)
	v_pk_mul_f32 v[252:253], v[180:181], v[158:159] op_sel_hi:[1,0] neg_lo:[0,1] neg_hi:[0,1]
	v_pk_mul_f32 v[246:247], v[180:181], v[156:157] op_sel_hi:[1,0] neg_lo:[0,1] neg_hi:[0,1]
	v_pk_mul_f32 v[192:193], v[182:183], v[158:159] op_sel_hi:[1,0] neg_lo:[0,1] neg_hi:[0,1]
	v_pk_mul_f32 v[230:231], v[182:183], v[156:157] op_sel_hi:[1,0] neg_lo:[0,1] neg_hi:[0,1]
	v_pk_fma_f32 v[110:111], v[110:111], v[176:177], v[252:253]
	v_pk_fma_f32 v[126:127], v[126:127], v[176:177], v[246:247]
	v_pk_fma_f32 v[112:113], v[112:113], v[178:179], v[192:193]
	v_pk_fma_f32 v[128:129], v[128:129], v[178:179], v[230:231]
	v_pk_fma_f32 v[126:127], v[132:133], v[184:185], v[126:127] op_sel_hi:[0,1,1]
	v_pk_fma_f32 v[128:129], v[132:133], v[186:187], v[128:129] op_sel_hi:[0,1,1]
	ds_read_b128 v[176:179], v232 offset:320
	ds_read_b128 v[180:183], v232 offset:576
	ds_read_b128 v[184:187], v232 offset:832
	s_waitcnt lgkmcnt(9)
	v_pk_mul_f32 v[252:253], v[214:215], v[158:159] op_sel_hi:[1,0] neg_lo:[0,1] neg_hi:[0,1]
	v_pk_mul_f32 v[246:247], v[214:215], v[156:157] op_sel_hi:[1,0] neg_lo:[0,1] neg_hi:[0,1]
	v_pk_mul_f32 v[192:193], v[216:217], v[158:159] op_sel_hi:[1,0] neg_lo:[0,1] neg_hi:[0,1]
	v_pk_mul_f32 v[230:231], v[216:217], v[156:157] op_sel_hi:[1,0] neg_lo:[0,1] neg_hi:[0,1]
	v_pk_fma_f32 v[98:99], v[98:99], v[188:189], v[252:253]
	v_pk_fma_f32 v[122:123], v[122:123], v[188:189], v[246:247]
	v_pk_fma_f32 v[100:101], v[100:101], v[190:191], v[192:193]
	v_pk_fma_f32 v[124:125], v[124:125], v[190:191], v[230:231]
	v_pk_fma_f32 v[122:123], v[132:133], v[218:219], v[122:123] op_sel_hi:[0,1,1]
	v_pk_fma_f32 v[124:125], v[132:133], v[220:221], v[124:125] op_sel_hi:[0,1,1]
	ds_read_b128 v[188:191], v232 offset:336
	ds_read_b128 v[214:217], v232 offset:592
	ds_read_b128 v[218:221], v232 offset:848
	s_waitcnt lgkmcnt(9)
	v_pk_mul_f32 v[252:253], v[226:227], v[158:159] op_sel_hi:[1,0] neg_lo:[0,1] neg_hi:[0,1]
	v_pk_mul_f32 v[246:247], v[226:227], v[156:157] op_sel_hi:[1,0] neg_lo:[0,1] neg_hi:[0,1]
	v_pk_mul_f32 v[192:193], v[228:229], v[158:159] op_sel_hi:[1,0] neg_lo:[0,1] neg_hi:[0,1]
	v_pk_mul_f32 v[230:231], v[228:229], v[156:157] op_sel_hi:[1,0] neg_lo:[0,1] neg_hi:[0,1]
	v_pk_fma_f32 v[90:91], v[90:91], v[222:223], v[252:253]
	v_pk_fma_f32 v[118:119], v[118:119], v[222:223], v[246:247]
	v_pk_fma_f32 v[92:93], v[92:93], v[224:225], v[192:193]
	v_pk_fma_f32 v[120:121], v[120:121], v[224:225], v[230:231]
	v_pk_fma_f32 v[118:119], v[132:133], v[160:161], v[118:119] op_sel_hi:[0,1,1]
	v_pk_fma_f32 v[120:121], v[132:133], v[162:163], v[120:121] op_sel_hi:[0,1,1]
	ds_read_b128 v[222:225], v232 offset:352
	ds_read_b128 v[226:229], v232 offset:608
	ds_read_b128 v[160:163], v232 offset:864
	s_waitcnt lgkmcnt(9)
	v_pk_mul_f32 v[252:253], v[168:169], v[158:159] op_sel_hi:[1,0] neg_lo:[0,1] neg_hi:[0,1]
	v_pk_mul_f32 v[246:247], v[168:169], v[156:157] op_sel_hi:[1,0] neg_lo:[0,1] neg_hi:[0,1]
	v_pk_mul_f32 v[192:193], v[170:171], v[158:159] op_sel_hi:[1,0] neg_lo:[0,1] neg_hi:[0,1]
	v_pk_mul_f32 v[230:231], v[170:171], v[156:157] op_sel_hi:[1,0] neg_lo:[0,1] neg_hi:[0,1]
	v_pk_fma_f32 v[82:83], v[82:83], v[164:165], v[252:253]
	v_pk_fma_f32 v[114:115], v[114:115], v[164:165], v[246:247]
	v_pk_fma_f32 v[84:85], v[84:85], v[166:167], v[192:193]
	v_pk_fma_f32 v[116:117], v[116:117], v[166:167], v[230:231]
	v_pk_fma_f32 v[114:115], v[132:133], v[172:173], v[114:115] op_sel_hi:[0,1,1]
	v_pk_fma_f32 v[116:117], v[132:133], v[174:175], v[116:117] op_sel_hi:[0,1,1]
	ds_read_b128 v[164:167], v232 offset:368
	ds_read_b128 v[168:171], v232 offset:624
	ds_read_b128 v[172:175], v232 offset:880
	s_waitcnt lgkmcnt(9)
	v_pk_mul_f32 v[252:253], v[180:181], v[158:159] op_sel_hi:[1,0] neg_lo:[0,1] neg_hi:[0,1]
	v_pk_mul_f32 v[246:247], v[180:181], v[156:157] op_sel_hi:[1,0] neg_lo:[0,1] neg_hi:[0,1]
	v_pk_mul_f32 v[192:193], v[182:183], v[158:159] op_sel_hi:[1,0] neg_lo:[0,1] neg_hi:[0,1]
	v_pk_mul_f32 v[230:231], v[182:183], v[156:157] op_sel_hi:[1,0] neg_lo:[0,1] neg_hi:[0,1]
	v_pk_fma_f32 v[74:75], v[74:75], v[176:177], v[252:253]
	v_pk_fma_f32 v[106:107], v[106:107], v[176:177], v[246:247]
	v_pk_fma_f32 v[76:77], v[76:77], v[178:179], v[192:193]
	v_pk_fma_f32 v[108:109], v[108:109], v[178:179], v[230:231]
	v_pk_fma_f32 v[106:107], v[132:133], v[184:185], v[106:107] op_sel_hi:[0,1,1]
	v_pk_fma_f32 v[108:109], v[132:133], v[186:187], v[108:109] op_sel_hi:[0,1,1]
	ds_read_b128 v[176:179], v232 offset:384
	ds_read_b128 v[180:183], v232 offset:640
	ds_read_b128 v[184:187], v232 offset:896
	s_waitcnt lgkmcnt(9)
	v_pk_mul_f32 v[252:253], v[214:215], v[158:159] op_sel_hi:[1,0] neg_lo:[0,1] neg_hi:[0,1]
	v_pk_mul_f32 v[246:247], v[214:215], v[156:157] op_sel_hi:[1,0] neg_lo:[0,1] neg_hi:[0,1]
	v_pk_mul_f32 v[192:193], v[216:217], v[158:159] op_sel_hi:[1,0] neg_lo:[0,1] neg_hi:[0,1]
	v_pk_mul_f32 v[230:231], v[216:217], v[156:157] op_sel_hi:[1,0] neg_lo:[0,1] neg_hi:[0,1]
	v_pk_fma_f32 v[66:67], v[66:67], v[188:189], v[252:253]
	v_pk_fma_f32 v[102:103], v[102:103], v[188:189], v[246:247]
	v_pk_fma_f32 v[68:69], v[68:69], v[190:191], v[192:193]
	v_pk_fma_f32 v[104:105], v[104:105], v[190:191], v[230:231]
	v_pk_fma_f32 v[102:103], v[132:133], v[218:219], v[102:103] op_sel_hi:[0,1,1]
	v_pk_fma_f32 v[104:105], v[132:133], v[220:221], v[104:105] op_sel_hi:[0,1,1]
	ds_read_b128 v[188:191], v232 offset:400
	ds_read_b128 v[214:217], v232 offset:656
	ds_read_b128 v[218:221], v232 offset:912
	s_waitcnt lgkmcnt(9)
; #define P1_BLK(b) { f32x16s w_, a_, k_; SL3(w_, a_, k_, o, 256 + 64 * (b), 512 + 64 * (b), 768 + 64 * (b)); _Pragma("unroll") for (int p_ = 0; p_ < 8; ++p_) { \
;                 f32x2 s = SP[8 * (b) + p_] * PR(w_, p_); s += savP * PR(a_, p_); SP[8 * (b) + p_] = s; \
;                 f32x2 l = SLs[8 * (b) + p_] * PR(w_, p_); l += savL * PR(a_, p_); l += vv * PR(k_, p_); SLs[8 * (b) + p_] = l; } }
; __device__ __forceinline__ void scan_pass1(const Ctx&, unsigned char* ws, int rot) { const Ctx c = mk_ctx();
;     ...
;             P1_BLK(0) P1_BLK(1) P1_BLK(2) P1_BLK(3)
	v_pk_mul_f32 v[252:253], v[226:227], v[158:159] op_sel_hi:[1,0] neg_lo:[0,1] neg_hi:[0,1]
	v_pk_mul_f32 v[246:247], v[226:227], v[156:157] op_sel_hi:[1,0] neg_lo:[0,1] neg_hi:[0,1]
	v_pk_mul_f32 v[192:193], v[228:229], v[158:159] op_sel_hi:[1,0] neg_lo:[0,1] neg_hi:[0,1]
	v_pk_mul_f32 v[230:231], v[228:229], v[156:157] op_sel_hi:[1,0] neg_lo:[0,1] neg_hi:[0,1]
	v_pk_fma_f32 v[58:59], v[58:59], v[222:223], v[252:253]
	v_pk_fma_f32 v[94:95], v[94:95], v[222:223], v[246:247]
	v_pk_fma_f32 v[60:61], v[60:61], v[224:225], v[192:193]
	v_pk_fma_f32 v[96:97], v[96:97], v[224:225], v[230:231]
	v_pk_fma_f32 v[94:95], v[132:133], v[160:161], v[94:95] op_sel_hi:[0,1,1]
	v_pk_fma_f32 v[96:97], v[132:133], v[162:163], v[96:97] op_sel_hi:[0,1,1]
	ds_read_b128 v[222:225], v232 offset:416
	ds_read_b128 v[226:229], v232 offset:672
	ds_read_b128 v[160:163], v232 offset:928
	s_waitcnt lgkmcnt(9)
	v_pk_mul_f32 v[252:253], v[168:169], v[158:159] op_sel_hi:[1,0] neg_lo:[0,1] neg_hi:[0,1]
	v_pk_mul_f32 v[246:247], v[168:169], v[156:157] op_sel_hi:[1,0] neg_lo:[0,1] neg_hi:[0,1]
	v_pk_mul_f32 v[192:193], v[170:171], v[158:159] op_sel_hi:[1,0] neg_lo:[0,1] neg_hi:[0,1]
	v_pk_mul_f32 v[230:231], v[170:171], v[156:157] op_sel_hi:[1,0] neg_lo:[0,1] neg_hi:[0,1]
	v_pk_fma_f32 v[50:51], v[50:51], v[164:165], v[252:253]
	v_pk_fma_f32 v[86:87], v[86:87], v[164:165], v[246:247]
	v_pk_fma_f32 v[52:53], v[52:53], v[166:167], v[192:193]
	v_pk_fma_f32 v[88:89], v[88:89], v[166:167], v[230:231]
	v_pk_fma_f32 v[86:87], v[132:133], v[172:173], v[86:87] op_sel_hi:[0,1,1]
	v_pk_fma_f32 v[88:89], v[132:133], v[174:175], v[88:89] op_sel_hi:[0,1,1]
	ds_read_b128 v[164:167], v232 offset:432
	ds_read_b128 v[168:171], v232 offset:688
	ds_read_b128 v[172:175], v232 offset:944
	s_waitcnt lgkmcnt(9)
	v_pk_mul_f32 v[252:253], v[180:181], v[158:159] op_sel_hi:[1,0] neg_lo:[0,1] neg_hi:[0,1]
	v_pk_mul_f32 v[246:247], v[180:181], v[156:157] op_sel_hi:[1,0] neg_lo:[0,1] neg_hi:[0,1]
	v_pk_mul_f32 v[192:193], v[182:183], v[158:159] op_sel_hi:[1,0] neg_lo:[0,1] neg_hi:[0,1]
	v_pk_mul_f32 v[230:231], v[182:183], v[156:157] op_sel_hi:[1,0] neg_lo:[0,1] neg_hi:[0,1]
	v_pk_fma_f32 v[42:43], v[42:43], v[176:177], v[252:253]
	v_pk_fma_f32 v[78:79], v[78:79], v[176:177], v[246:247]
	v_pk_fma_f32 v[44:45], v[44:45], v[178:179], v[192:193]
	v_pk_fma_f32 v[80:81], v[80:81], v[178:179], v[230:231]
	v_pk_fma_f32 v[78:79], v[132:133], v[184:185], v[78:79] op_sel_hi:[0,1,1]
	v_pk_fma_f32 v[80:81], v[132:133], v[186:187], v[80:81] op_sel_hi:[0,1,1]
	ds_read_b128 v[176:179], v232 offset:448
	ds_read_b128 v[180:183], v232 offset:704
	ds_read_b128 v[184:187], v232 offset:960
	s_waitcnt lgkmcnt(9)
	v_pk_mul_f32 v[252:253], v[214:215], v[158:159] op_sel_hi:[1,0] neg_lo:[0,1] neg_hi:[0,1]
	v_pk_mul_f32 v[246:247], v[214:215], v[156:157] op_sel_hi:[1,0] neg_lo:[0,1] neg_hi:[0,1]
	v_pk_mul_f32 v[192:193], v[216:217], v[158:159] op_sel_hi:[1,0] neg_lo:[0,1] neg_hi:[0,1]
	v_pk_mul_f32 v[230:231], v[216:217], v[156:157] op_sel_hi:[1,0] neg_lo:[0,1] neg_hi:[0,1]
	v_pk_fma_f32 v[34:35], v[34:35], v[188:189], v[252:253]
	v_pk_fma_f32 v[70:71], v[70:71], v[188:189], v[246:247]
	v_pk_fma_f32 v[36:37], v[36:37], v[190:191], v[192:193]
	v_pk_fma_f32 v[72:73], v[72:73], v[190:191], v[230:231]
	v_pk_fma_f32 v[70:71], v[132:133], v[218:219], v[70:71] op_sel_hi:[0,1,1]
	v_pk_fma_f32 v[72:73], v[132:133], v[220:221], v[72:73] op_sel_hi:[0,1,1]
	ds_read_b128 v[188:191], v232 offset:464
	ds_read_b128 v[214:217], v232 offset:720
	ds_read_b128 v[218:221], v232 offset:976
	s_waitcnt lgkmcnt(9)
	v_pk_mul_f32 v[252:253], v[226:227], v[158:159] op_sel_hi:[1,0] neg_lo:[0,1] neg_hi:[0,1]
	v_pk_mul_f32 v[246:247], v[226:227], v[156:157] op_sel_hi:[1,0] neg_lo:[0,1] neg_hi:[0,1]
	v_pk_mul_f32 v[192:193], v[228:229], v[158:159] op_sel_hi:[1,0] neg_lo:[0,1] neg_hi:[0,1]
	v_pk_mul_f32 v[230:231], v[228:229], v[156:157] op_sel_hi:[1,0] neg_lo:[0,1] neg_hi:[0,1]
	v_pk_fma_f32 v[26:27], v[26:27], v[222:223], v[252:253]
	v_pk_fma_f32 v[62:63], v[62:63], v[222:223], v[246:247]
	v_pk_fma_f32 v[28:29], v[28:29], v[224:225], v[192:193]
	v_pk_fma_f32 v[64:65], v[64:65], v[224:225], v[230:231]
	v_pk_fma_f32 v[62:63], v[132:133], v[160:161], v[62:63] op_sel_hi:[0,1,1]
	v_pk_fma_f32 v[64:65], v[132:133], v[162:163], v[64:65] op_sel_hi:[0,1,1]
	ds_read_b128 v[222:225], v232 offset:480
	ds_read_b128 v[226:229], v232 offset:736
	ds_read_b128 v[160:163], v232 offset:992
	s_waitcnt lgkmcnt(9)
	v_pk_mul_f32 v[252:253], v[168:169], v[158:159] op_sel_hi:[1,0] neg_lo:[0,1] neg_hi:[0,1]
	v_pk_mul_f32 v[246:247], v[168:169], v[156:157] op_sel_hi:[1,0] neg_lo:[0,1] neg_hi:[0,1]
	v_pk_mul_f32 v[192:193], v[170:171], v[158:159] op_sel_hi:[1,0] neg_lo:[0,1] neg_hi:[0,1]
	v_pk_mul_f32 v[230:231], v[170:171], v[156:157] op_sel_hi:[1,0] neg_lo:[0,1] neg_hi:[0,1]
	v_pk_fma_f32 v[22:23], v[22:23], v[164:165], v[252:253]
	v_pk_fma_f32 v[54:55], v[54:55], v[164:165], v[246:247]
	v_pk_fma_f32 v[24:25], v[24:25], v[166:167], v[192:193]
	v_pk_fma_f32 v[56:57], v[56:57], v[166:167], v[230:231]
	v_pk_fma_f32 v[54:55], v[132:133], v[172:173], v[54:55] op_sel_hi:[0,1,1]
	v_pk_fma_f32 v[56:57], v[132:133], v[174:175], v[56:57] op_sel_hi:[0,1,1]
	ds_read_b128 v[164:167], v232 offset:496
	ds_read_b128 v[168:171], v232 offset:752
	ds_read_b128 v[172:175], v232 offset:1008
	s_waitcnt lgkmcnt(9)
; #define P1_BLK(b) { f32x16s w_, a_, k_; SL3(w_, a_, k_, o, 256 + 64 * (b), 512 + 64 * (b), 768 + 64 * (b)); _Pragma("unroll") for (int p_ = 0; p_ < 8; ++p_) { \
;                 f32x2 s = SP[8 * (b) + p_] * PR(w_, p_); s += savP * PR(a_, p_); SP[8 * (b) + p_] = s; \
;                 f32x2 l = SLs[8 * (b) + p_] * PR(w_, p_); l += savL * PR(a_, p_); l += vv * PR(k_, p_); SLs[8 * (b) + p_] = l; } }
; __device__ __forceinline__ void scan_pass1(const Ctx&, unsigned char* ws, int rot) { const Ctx c = mk_ctx();
;     ...
;             P1_BLK(0) P1_BLK(1) P1_BLK(2) P1_BLK(3)
;     ...
;         }
;         float* dst = PL + (((size_t)chain * NCH + cc) * 2) * 4096 + lane * 64;
; #pragma unroll
;         for (int j = 0; j < 16; ++j) { *(f32x4*)(dst + 4 * j) = (f32x4){SP[2 * j].x, SP[2 * j].y, SP[2 * j + 1].x, SP[2 * j + 1].y}; *(f32x4*)(dst + 4096 + 4 * j) = (f32x4){SLs[2 * j].x, SLs[2 * j].y, SLs[2 * j + 1].x, SLs[2 * j + 1].y}; }
	v_pk_mul_f32 v[252:253], v[180:181], v[158:159] op_sel_hi:[1,0] neg_lo:[0,1] neg_hi:[0,1]
	v_pk_mul_f32 v[246:247], v[180:181], v[156:157] op_sel_hi:[1,0] neg_lo:[0,1] neg_hi:[0,1]
	v_pk_mul_f32 v[192:193], v[182:183], v[158:159] op_sel_hi:[1,0] neg_lo:[0,1] neg_hi:[0,1]
	v_pk_mul_f32 v[230:231], v[182:183], v[156:157] op_sel_hi:[1,0] neg_lo:[0,1] neg_hi:[0,1]
	v_pk_fma_f32 v[14:15], v[14:15], v[176:177], v[252:253]
	v_pk_fma_f32 v[46:47], v[46:47], v[176:177], v[246:247]
	v_pk_fma_f32 v[16:17], v[16:17], v[178:179], v[192:193]
	v_pk_fma_f32 v[48:49], v[48:49], v[178:179], v[230:231]
	v_pk_fma_f32 v[46:47], v[132:133], v[184:185], v[46:47] op_sel_hi:[0,1,1]
	v_pk_fma_f32 v[48:49], v[132:133], v[186:187], v[48:49] op_sel_hi:[0,1,1]
	s_waitcnt lgkmcnt(6)
	v_pk_mul_f32 v[252:253], v[214:215], v[158:159] op_sel_hi:[1,0] neg_lo:[0,1] neg_hi:[0,1]
	v_pk_mul_f32 v[246:247], v[214:215], v[156:157] op_sel_hi:[1,0] neg_lo:[0,1] neg_hi:[0,1]
	v_pk_mul_f32 v[192:193], v[216:217], v[158:159] op_sel_hi:[1,0] neg_lo:[0,1] neg_hi:[0,1]
	v_pk_mul_f32 v[230:231], v[216:217], v[156:157] op_sel_hi:[1,0] neg_lo:[0,1] neg_hi:[0,1]
	v_pk_fma_f32 v[10:11], v[10:11], v[188:189], v[252:253]
	v_pk_fma_f32 v[38:39], v[38:39], v[188:189], v[246:247]
	v_pk_fma_f32 v[12:13], v[12:13], v[190:191], v[192:193]
	v_pk_fma_f32 v[40:41], v[40:41], v[190:191], v[230:231]
	v_pk_fma_f32 v[38:39], v[132:133], v[218:219], v[38:39] op_sel_hi:[0,1,1]
	v_pk_fma_f32 v[40:41], v[132:133], v[220:221], v[40:41] op_sel_hi:[0,1,1]
	s_waitcnt lgkmcnt(3)
	v_pk_mul_f32 v[252:253], v[226:227], v[158:159] op_sel_hi:[1,0] neg_lo:[0,1] neg_hi:[0,1]
	v_pk_mul_f32 v[246:247], v[226:227], v[156:157] op_sel_hi:[1,0] neg_lo:[0,1] neg_hi:[0,1]
	v_pk_mul_f32 v[192:193], v[228:229], v[158:159] op_sel_hi:[1,0] neg_lo:[0,1] neg_hi:[0,1]
	v_pk_mul_f32 v[230:231], v[228:229], v[156:157] op_sel_hi:[1,0] neg_lo:[0,1] neg_hi:[0,1]
	v_pk_fma_f32 v[6:7], v[6:7], v[222:223], v[252:253]
	v_pk_fma_f32 v[30:31], v[30:31], v[222:223], v[246:247]
	v_pk_fma_f32 v[8:9], v[8:9], v[224:225], v[192:193]
	v_pk_fma_f32 v[32:33], v[32:33], v[224:225], v[230:231]
	v_pk_fma_f32 v[30:31], v[132:133], v[160:161], v[30:31] op_sel_hi:[0,1,1]
	v_pk_fma_f32 v[32:33], v[132:133], v[162:163], v[32:33] op_sel_hi:[0,1,1]
	s_waitcnt lgkmcnt(0)
	v_pk_mul_f32 v[252:253], v[168:169], v[158:159] op_sel_hi:[1,0] neg_lo:[0,1] neg_hi:[0,1]
	v_pk_mul_f32 v[246:247], v[168:169], v[156:157] op_sel_hi:[1,0] neg_lo:[0,1] neg_hi:[0,1]
	v_pk_mul_f32 v[192:193], v[170:171], v[158:159] op_sel_hi:[1,0] neg_lo:[0,1] neg_hi:[0,1]
	v_pk_mul_f32 v[230:231], v[170:171], v[156:157] op_sel_hi:[1,0] neg_lo:[0,1] neg_hi:[0,1]
	v_pk_fma_f32 v[2:3], v[2:3], v[164:165], v[252:253]
	v_pk_fma_f32 v[18:19], v[18:19], v[164:165], v[246:247]
	v_pk_fma_f32 v[4:5], v[4:5], v[166:167], v[192:193]
	v_pk_fma_f32 v[20:21], v[20:21], v[166:167], v[230:231]
	v_pk_fma_f32 v[18:19], v[132:133], v[172:173], v[18:19] op_sel_hi:[0,1,1]
	v_pk_fma_f32 v[20:21], v[132:133], v[174:175], v[20:21] op_sel_hi:[0,1,1]
	v_lshl_add_u64 v[142:143], v[142:143], 0, s[94:95]
	s_add_i32 s30, s30, 1
	s_add_u32 s28, s28, 0x500
	s_addc_u32 s29, s29, 0
	s_cmp_eq_u32 s28, 0x28000
	s_cbranch_scc0 .LBB0_1918
	s_lshl_b64 s[4:5], s[26:27], 21
	s_add_u32 s6, s0, s4
	s_addc_u32 s7, s1, s5
	s_lshl_b64 s[4:5], s[24:25], 15
	s_add_u32 s4, s6, s4
	s_addc_u32 s5, s7, s5
	s_waitcnt vmcnt(0)
	v_lshl_add_u64 v[130:131], s[4:5], 0, v[150:151]
	s_movk_i32 s6, 0x4000
	global_store_dwordx4 v150, v[110:113], s[4:5]
	s_nop 1
	v_add_co_u32_e32 v110, vcc, s6, v130
	s_nop 1
	v_addc_co_u32_e32 v111, vcc, 0, v131, vcc
	global_store_dwordx4 v[110:111], v[126:129], off
	global_store_dwordx4 v150, v[98:101], s[4:5] offset:16
	global_store_dwordx4 v[110:111], v[122:125], off offset:16
	global_store_dwordx4 v150, v[90:93], s[4:5] offset:32
	global_store_dwordx4 v[110:111], v[118:121], off offset:32
	global_store_dwordx4 v150, v[82:85], s[4:5] offset:48
	global_store_dwordx4 v[110:111], v[114:117], off offset:48
	global_store_dwordx4 v150, v[74:77], s[4:5] offset:64
	global_store_dwordx4 v[110:111], v[106:109], off offset:64
	global_store_dwordx4 v150, v[66:69], s[4:5] offset:80
	global_store_dwordx4 v[110:111], v[102:105], off offset:80
	global_store_dwordx4 v150, v[58:61], s[4:5] offset:96
	global_store_dwordx4 v[110:111], v[94:97], off offset:96
	global_store_dwordx4 v150, v[50:53], s[4:5] offset:112
	global_store_dwordx4 v[110:111], v[86:89], off offset:112
	global_store_dwordx4 v150, v[42:45], s[4:5] offset:128
	global_store_dwordx4 v[110:111], v[78:81], off offset:128
	global_store_dwordx4 v150, v[34:37], s[4:5] offset:144
	global_store_dwordx4 v[110:111], v[70:73], off offset:144
	global_store_dwordx4 v150, v[26:29], s[4:5] offset:160
	global_store_dwordx4 v[110:111], v[62:65], off offset:160
	global_store_dwordx4 v150, v[22:25], s[4:5] offset:176
	global_store_dwordx4 v[110:111], v[54:57], off offset:176
	global_store_dwordx4 v150, v[14:17], s[4:5] offset:192
	global_store_dwordx4 v[110:111], v[46:49], off offset:192
	global_store_dwordx4 v150, v[10:13], s[4:5] offset:208
	global_store_dwordx4 v[110:111], v[38:41], off offset:208
	global_store_dwordx4 v150, v[6:9], s[4:5] offset:224
	global_store_dwordx4 v[110:111], v[30:33], off offset:224
	global_store_dwordx4 v150, v[2:5], s[4:5] offset:240
	v_readlane_b32 s4, v254, 31
	s_add_i32 s33, s33, s4
	v_cmp_eq_u32_e32 vcc, 0, v206
	s_nop 1
	v_cndmask_b32_e64 v1, 0, 1.0, vcc
	v_cmp_eq_u32_e32 vcc, 1, v206
	s_nop 1
; __device__ __forceinline__ void scan_pass1(const Ctx&, unsigned char* ws, int rot) { const Ctx c = mk_ctx();
;     ...
;     for (int task = (int)((blockIdx.x + (rot ? gridDim.x / 2 : 0)) % gridDim.x) * 4 + c.wid; task < 16 * (NCH - 1); task += gridDim.x * 4) {
;         const int cc = task % (NCH - 1), chain = task / (NCH - 1);
;         f32x2 SP[32], SLs[32];
; #pragma unroll
;         for (int j = 0; j < 32; ++j) { SP[j].x = (2 * j == lane) ? 1.f : 0.f; SP[j].y = (2 * j + 1 == lane) ? 1.f : 0.f; SLs[j] = (f32x2){0.f, 0.f}; }
;     ...
;         for (int j = 0; j < 16; ++j) { *(f32x4*)(dst + 4 * j) = (f32x4){SP[2 * j].x, SP[2 * j].y, SP[2 * j + 1].x, SP[2 * j + 1].y}; *(f32x4*)(dst + 4096 + 4 * j) = (f32x4){SLs[2 * j].x, SLs[2 * j].y, SLs[2 * j + 1].x, SLs[2 * j + 1].y}; }
;     }
;     if (pfdummy == 1.2345e-30f) PL[0] = pfdummy;
	v_cndmask_b32_e64 v160, 0, 1.0, vcc
	v_cmp_eq_u32_e32 vcc, 2, v206
	s_nop 1
	v_cndmask_b32_e64 v161, 0, 1.0, vcc
	v_cmp_eq_u32_e32 vcc, 3, v206
	s_nop 1
	v_cndmask_b32_e64 v162, 0, 1.0, vcc
	v_cmp_eq_u32_e32 vcc, 4, v206
	s_nop 1
	v_cndmask_b32_e64 v163, 0, 1.0, vcc
	v_cmp_eq_u32_e32 vcc, 5, v206
	s_nop 1
	v_cndmask_b32_e64 v164, 0, 1.0, vcc
	v_cmp_eq_u32_e32 vcc, 6, v206
	s_nop 1
	v_cndmask_b32_e64 v165, 0, 1.0, vcc
	v_cmp_eq_u32_e32 vcc, 7, v206
	s_nop 1
	v_cndmask_b32_e64 v166, 0, 1.0, vcc
	v_cmp_eq_u32_e32 vcc, 8, v206
	s_nop 1
	v_cndmask_b32_e64 v167, 0, 1.0, vcc
	v_cmp_eq_u32_e32 vcc, 9, v206
	s_nop 1
	v_cndmask_b32_e64 v168, 0, 1.0, vcc
	v_cmp_eq_u32_e32 vcc, 10, v206
	s_nop 1
	v_cndmask_b32_e64 v169, 0, 1.0, vcc
	v_cmp_eq_u32_e32 vcc, 11, v206
	s_nop 1
	v_cndmask_b32_e64 v170, 0, 1.0, vcc
	v_cmp_eq_u32_e32 vcc, 12, v206
	s_nop 1
	v_cndmask_b32_e64 v171, 0, 1.0, vcc
	v_cmp_eq_u32_e32 vcc, 13, v206
	s_nop 1
	v_cndmask_b32_e64 v172, 0, 1.0, vcc
	v_cmp_eq_u32_e32 vcc, 14, v206
	s_nop 1
	v_cndmask_b32_e64 v173, 0, 1.0, vcc
	v_cmp_eq_u32_e32 vcc, 15, v206
	s_nop 1
	v_cndmask_b32_e64 v174, 0, 1.0, vcc
	v_cmp_eq_u32_e32 vcc, 16, v206
	s_nop 1
	v_cndmask_b32_e64 v175, 0, 1.0, vcc
	v_cmp_eq_u32_e32 vcc, 17, v206
	s_nop 1
	v_cndmask_b32_e64 v176, 0, 1.0, vcc
	v_cmp_eq_u32_e32 vcc, 18, v206
	s_nop 1
	v_cndmask_b32_e64 v177, 0, 1.0, vcc
	v_cmp_eq_u32_e32 vcc, 19, v206
	s_nop 1
	v_cndmask_b32_e64 v178, 0, 1.0, vcc
	v_cmp_eq_u32_e32 vcc, 20, v206
	s_nop 1
	v_cndmask_b32_e64 v179, 0, 1.0, vcc
	v_cmp_eq_u32_e32 vcc, 21, v206
	s_nop 1
	v_cndmask_b32_e64 v180, 0, 1.0, vcc
	v_cmp_eq_u32_e32 vcc, 22, v206
	s_nop 1
	v_cndmask_b32_e64 v181, 0, 1.0, vcc
	v_cmp_eq_u32_e32 vcc, 23, v206
	s_nop 1
	v_cndmask_b32_e64 v182, 0, 1.0, vcc
	v_cmp_eq_u32_e32 vcc, 24, v206
	s_nop 1
	v_cndmask_b32_e64 v183, 0, 1.0, vcc
	v_cmp_eq_u32_e32 vcc, 25, v206
	s_nop 1
	v_cndmask_b32_e64 v184, 0, 1.0, vcc
	v_cmp_eq_u32_e32 vcc, 26, v206
	s_nop 1
	v_cndmask_b32_e64 v185, 0, 1.0, vcc
	v_cmp_eq_u32_e32 vcc, 27, v206
	s_nop 1
	v_cndmask_b32_e64 v186, 0, 1.0, vcc
	v_cmp_eq_u32_e32 vcc, 28, v206
	s_nop 1
	v_cndmask_b32_e64 v187, 0, 1.0, vcc
	v_cmp_eq_u32_e32 vcc, 29, v206
	s_nop 1
	v_cndmask_b32_e64 v188, 0, 1.0, vcc
	v_cmp_eq_u32_e32 vcc, 30, v206
	s_nop 1
	v_cndmask_b32_e64 v189, 0, 1.0, vcc
	v_cmp_eq_u32_e32 vcc, 31, v206
	s_nop 1
	v_cndmask_b32_e64 v190, 0, 1.0, vcc
	v_cmp_eq_u32_e32 vcc, 32, v206
	s_nop 1
	v_cndmask_b32_e64 v191, 0, 1.0, vcc
	v_cmp_eq_u32_e32 vcc, 33, v206
	s_nop 1
	v_cndmask_b32_e64 v192, 0, 1.0, vcc
	v_cmp_eq_u32_e32 vcc, 34, v206
	s_nop 1
	v_cndmask_b32_e64 v193, 0, 1.0, vcc
	v_cmp_eq_u32_e32 vcc, 35, v206
	s_nop 1
	v_cndmask_b32_e64 v214, 0, 1.0, vcc
	v_cmp_eq_u32_e32 vcc, 36, v206
	s_nop 1
	v_cndmask_b32_e64 v215, 0, 1.0, vcc
	v_cmp_eq_u32_e32 vcc, 37, v206
	s_nop 1
	v_cndmask_b32_e64 v216, 0, 1.0, vcc
	v_cmp_eq_u32_e32 vcc, 38, v206
	s_nop 1
	v_cndmask_b32_e64 v217, 0, 1.0, vcc
	v_cmp_eq_u32_e32 vcc, 39, v206
	s_nop 1
	v_cndmask_b32_e64 v218, 0, 1.0, vcc
	v_cmp_eq_u32_e32 vcc, 40, v206
	s_nop 1
	v_cndmask_b32_e64 v219, 0, 1.0, vcc
	v_cmp_eq_u32_e32 vcc, 41, v206
	s_nop 1
	v_cndmask_b32_e64 v220, 0, 1.0, vcc
	v_cmp_eq_u32_e32 vcc, 42, v206
	s_nop 1
	v_cndmask_b32_e64 v221, 0, 1.0, vcc
	v_cmp_eq_u32_e32 vcc, 43, v206
	s_nop 1
	v_cndmask_b32_e64 v222, 0, 1.0, vcc
	v_cmp_eq_u32_e32 vcc, 44, v206
	s_nop 1
	v_cndmask_b32_e64 v223, 0, 1.0, vcc
	v_cmp_eq_u32_e32 vcc, 45, v206
	s_nop 1
	v_cndmask_b32_e64 v224, 0, 1.0, vcc
	v_cmp_eq_u32_e32 vcc, 46, v206
	s_nop 1
	v_cndmask_b32_e64 v225, 0, 1.0, vcc
	v_cmp_eq_u32_e32 vcc, 47, v206
	s_nop 1
	v_cndmask_b32_e64 v226, 0, 1.0, vcc
	v_cmp_eq_u32_e32 vcc, 48, v206
	s_nop 1
	v_cndmask_b32_e64 v227, 0, 1.0, vcc
	v_cmp_eq_u32_e32 vcc, 49, v206
	s_nop 1
	v_cndmask_b32_e64 v228, 0, 1.0, vcc
	v_cmp_eq_u32_e32 vcc, 50, v206
	s_nop 1
	v_cndmask_b32_e64 v229, 0, 1.0, vcc
	v_cmp_eq_u32_e32 vcc, 51, v206
	s_nop 1
	v_cndmask_b32_e64 v230, 0, 1.0, vcc
	v_cmp_eq_u32_e32 vcc, 52, v206
	s_nop 1
	v_cndmask_b32_e64 v231, 0, 1.0, vcc
	v_cmp_eq_u32_e32 vcc, 53, v206
	s_nop 1
	v_cndmask_b32_e64 v232, 0, 1.0, vcc
	v_cmp_eq_u32_e32 vcc, 54, v206
	s_nop 1
	v_cndmask_b32_e64 v233, 0, 1.0, vcc
	v_cmp_eq_u32_e32 vcc, 55, v206
	s_nop 1
	v_cndmask_b32_e64 v234, 0, 1.0, vcc
	v_cmp_eq_u32_e32 vcc, 56, v206
	s_nop 1
	v_cndmask_b32_e64 v235, 0, 1.0, vcc
	v_cmp_eq_u32_e32 vcc, 57, v206
	s_nop 1
	v_cndmask_b32_e64 v236, 0, 1.0, vcc
	v_cmp_eq_u32_e32 vcc, 58, v206
	s_nop 1
	v_cndmask_b32_e64 v237, 0, 1.0, vcc
	v_cmp_eq_u32_e32 vcc, 59, v206
	s_nop 1
	v_cndmask_b32_e64 v238, 0, 1.0, vcc
	v_cmp_eq_u32_e32 vcc, 60, v206
	s_nop 1
	v_cndmask_b32_e64 v239, 0, 1.0, vcc
	v_cmp_eq_u32_e32 vcc, 61, v206
	s_nop 1
	v_cndmask_b32_e64 v240, 0, 1.0, vcc
	v_cmp_eq_u32_e32 vcc, 62, v206
	s_nop 1
	v_cndmask_b32_e64 v241, 0, 1.0, vcc
	v_cmp_eq_u32_e32 vcc, 63, v206
	s_nop 1
	v_cndmask_b32_e64 v242, 0, 1.0, vcc
	s_cmpk_gt_i32 s33, 0x3ef
	global_store_dwordx4 v[110:111], v[18:21], off offset:240
	s_cbranch_scc0 .LBB0_1917
	s_mov_b32 s4, 0xdc84f20
	v_cmp_eq_f32_e32 vcc, s4, v244
	s_and_saveexec_b64 s[4:5], vcc
	v_readlane_b32 s80, v254, 56
	v_readlane_b32 s82, v254, 58
	v_readlane_b32 s84, v254, 60
	v_readlane_b32 s86, v254, 62
	v_readlane_b32 s81, v254, 57
	v_readlane_b32 s83, v254, 59
	v_readlane_b32 s85, v254, 61
	v_readlane_b32 s87, v254, 63
	s_mov_b32 s79, 0xc2200000
	s_mov_b32 s88, s20
	s_mov_b32 s90, s38
	s_mov_b32 s56, s39
	s_mov_b32 s57, s41
	s_mov_b32 s58, s43
	s_cbranch_execz .LBB0_1922
	global_store_dword v151, v205, s[0:1]
